# P12 epilogue: first conv weight/bias load batch issued ahead of the boundary-row stores (their acks no longer gate the loads); wait count raised by the 16 younger stores
# speedup vs baseline: 1.0034x; 1.0034x over previous
.Lmy_prio_skip5:
.LBB0_914:
	ds_read_b128 v[128:131], v187
	ds_read_b128 v[132:135], v187 offset:1024
	ds_read_b128 v[136:139], v187 offset:2048
	ds_read_b128 v[140:143], v187 offset:3072
	ds_read_b128 v[144:147], v188
	ds_read_b128 v[148:151], v188 offset:1024
	ds_read_b128 v[152:155], v188 offset:2048
	ds_read_b128 v[156:159], v188 offset:3072
	s_add_u32 s52, s50, 0x100
	s_addc_u32 s53, s51, 0
	s_cmp_eq_u32 s96, 60
	s_cselect_b32 s57, s41, s53
	s_cselect_b32 s56, s47, s52
	s_cselect_b32 s55, s39, s49
	s_cselect_b32 s54, s34, s35
	s_add_i32 m0, s67, 0xc000
	ds_read_b128 v[178:181], v189
	ds_read_b128 v[192:195], v189 offset:1024
	ds_read_b128 v[196:199], v189 offset:2048
	ds_read_b128 v[200:203], v189 offset:3072
	ds_read_b128 v[204:207], v189 offset:4096
	ds_read_b128 v[208:211], v189 offset:5120
	ds_read_b128 v[212:215], v189 offset:6144
	ds_read_b128 v[216:219], v189 offset:7168
	global_load_lds_dwordx4 v170, s[50:51]
	s_add_i32 m0, s67, 0xe000
	s_nop 0
	global_load_lds_dwordx4 v172, s[50:51]
	s_waitcnt vmcnt(8)
	s_waitcnt lgkmcnt(0)
	s_barrier
	s_waitcnt lgkmcnt(0)
	v_mfma_f32_16x16x32_bf16 v[124:127], v[128:131], v[178:181], v[124:127]
	v_mfma_f32_16x16x32_bf16 v[60:63], v[136:139], v[178:181], v[60:63]
	v_mfma_f32_16x16x32_bf16 v[116:119], v[128:131], v[196:199], v[116:119]
	v_mfma_f32_16x16x32_bf16 v[56:59], v[136:139], v[196:199], v[56:59]
	v_mfma_f32_16x16x32_bf16 v[108:111], v[128:131], v[204:207], v[108:111]
	v_mfma_f32_16x16x32_bf16 v[44:47], v[136:139], v[204:207], v[44:47]
	v_mfma_f32_16x16x32_bf16 v[104:107], v[128:131], v[212:215], v[104:107]
	v_mfma_f32_16x16x32_bf16 v[40:43], v[136:139], v[212:215], v[40:43]
	v_mfma_f32_16x16x32_bf16 v[124:127], v[132:135], v[192:195], v[124:127]
	v_mfma_f32_16x16x32_bf16 v[60:63], v[140:143], v[192:195], v[60:63]
	v_mfma_f32_16x16x32_bf16 v[116:119], v[132:135], v[200:203], v[116:119]
	v_mfma_f32_16x16x32_bf16 v[56:59], v[140:143], v[200:203], v[56:59]
	v_mfma_f32_16x16x32_bf16 v[108:111], v[132:135], v[208:211], v[108:111]
	v_mfma_f32_16x16x32_bf16 v[44:47], v[140:143], v[208:211], v[44:47]
	v_mfma_f32_16x16x32_bf16 v[104:107], v[132:135], v[216:219], v[104:107]
	v_mfma_f32_16x16x32_bf16 v[40:43], v[140:143], v[216:219], v[40:43]
	v_mfma_f32_16x16x32_bf16 v[120:123], v[144:147], v[178:181], v[120:123]
	v_mfma_f32_16x16x32_bf16 v[52:55], v[152:155], v[178:181], v[52:55]
	v_mfma_f32_16x16x32_bf16 v[112:115], v[144:147], v[196:199], v[112:115]
	v_mfma_f32_16x16x32_bf16 v[48:51], v[152:155], v[196:199], v[48:51]
	v_mfma_f32_16x16x32_bf16 v[100:103], v[144:147], v[204:207], v[100:103]
	v_mfma_f32_16x16x32_bf16 v[36:39], v[152:155], v[204:207], v[36:39]
	v_mfma_f32_16x16x32_bf16 v[96:99], v[144:147], v[212:215], v[96:99]
	v_mfma_f32_16x16x32_bf16 v[32:35], v[152:155], v[212:215], v[32:35]
	v_mfma_f32_16x16x32_bf16 v[120:123], v[148:151], v[192:195], v[120:123]
	v_mfma_f32_16x16x32_bf16 v[52:55], v[156:159], v[192:195], v[52:55]
	v_mfma_f32_16x16x32_bf16 v[112:115], v[148:151], v[200:203], v[112:115]
	v_mfma_f32_16x16x32_bf16 v[48:51], v[156:159], v[200:203], v[48:51]
	v_mfma_f32_16x16x32_bf16 v[100:103], v[148:151], v[208:211], v[100:103]
	v_mfma_f32_16x16x32_bf16 v[36:39], v[156:159], v[208:211], v[36:39]
	v_mfma_f32_16x16x32_bf16 v[96:99], v[148:151], v[216:219], v[96:99]
	v_mfma_f32_16x16x32_bf16 v[32:35], v[156:159], v[216:219], v[32:35]
	s_barrier
	s_add_i32 s50, s92, s66
	s_mov_b32 m0, s50
	ds_read_b128 v[178:181], v189 offset:16384
	ds_read_b128 v[192:195], v189 offset:17408
	ds_read_b128 v[196:199], v189 offset:18432
	ds_read_b128 v[200:203], v189 offset:19456
	ds_read_b128 v[204:207], v189 offset:20480
	ds_read_b128 v[208:211], v189 offset:21504
	ds_read_b128 v[212:215], v189 offset:22528
	ds_read_b128 v[216:219], v189 offset:23552
	global_load_lds_dwordx4 v164, s[54:55]
	s_add_i32 m0, s50, 0x2000
	s_add_u32 s50, s54, 0x100000
	v_lshl_add_u64 v[182:183], s[54:55], 0, v[168:169]
	s_addc_u32 s51, s55, 0
	s_add_i32 s97, s93, s66
	global_load_lds_dwordx4 v168, s[54:55]
	s_mov_b32 m0, s97
	global_load_lds_dwordx4 v164, s[50:51]
	s_add_i32 m0, s97, 0x2000
	s_nop 0
	global_load_lds_dwordx4 v168, s[50:51]
	s_mov_b32 m0, s67
	s_nop 0
	global_load_lds_dwordx4 v162, s[56:57]
	s_mov_b32 m0, s68
	s_nop 0
	global_load_lds_dwordx4 v166, s[56:57]
	s_waitcnt vmcnt(8)
	s_waitcnt lgkmcnt(0)
	s_barrier
	s_waitcnt lgkmcnt(0)
	v_mfma_f32_16x16x32_bf16 v[92:95], v[128:131], v[178:181], v[92:95]
	v_mfma_f32_16x16x32_bf16 v[28:31], v[136:139], v[178:181], v[28:31]
	v_mfma_f32_16x16x32_bf16 v[84:87], v[128:131], v[196:199], v[84:87]
	v_mfma_f32_16x16x32_bf16 v[24:27], v[136:139], v[196:199], v[24:27]
	v_mfma_f32_16x16x32_bf16 v[76:79], v[128:131], v[204:207], v[76:79]
	v_mfma_f32_16x16x32_bf16 v[12:15], v[136:139], v[204:207], v[12:15]
	v_mfma_f32_16x16x32_bf16 v[72:75], v[128:131], v[212:215], v[72:75]
	v_mfma_f32_16x16x32_bf16 v[8:11], v[136:139], v[212:215], v[8:11]
	v_mfma_f32_16x16x32_bf16 v[92:95], v[132:135], v[192:195], v[92:95]
	v_mfma_f32_16x16x32_bf16 v[28:31], v[140:143], v[192:195], v[28:31]
	v_mfma_f32_16x16x32_bf16 v[84:87], v[132:135], v[200:203], v[84:87]
	v_mfma_f32_16x16x32_bf16 v[24:27], v[140:143], v[200:203], v[24:27]
	v_mfma_f32_16x16x32_bf16 v[76:79], v[132:135], v[208:211], v[76:79]
	v_mfma_f32_16x16x32_bf16 v[12:15], v[140:143], v[208:211], v[12:15]
	v_mfma_f32_16x16x32_bf16 v[72:75], v[132:135], v[216:219], v[72:75]
	v_mfma_f32_16x16x32_bf16 v[8:11], v[140:143], v[216:219], v[8:11]
	v_mfma_f32_16x16x32_bf16 v[88:91], v[144:147], v[178:181], v[88:91]
	v_mfma_f32_16x16x32_bf16 v[20:23], v[152:155], v[178:181], v[20:23]
	v_mfma_f32_16x16x32_bf16 v[80:83], v[144:147], v[196:199], v[80:83]
	v_mfma_f32_16x16x32_bf16 v[16:19], v[152:155], v[196:199], v[16:19]
	v_mfma_f32_16x16x32_bf16 v[68:71], v[144:147], v[204:207], v[68:71]
	v_mfma_f32_16x16x32_bf16 v[4:7], v[152:155], v[204:207], v[4:7]
	v_mfma_f32_16x16x32_bf16 v[64:67], v[144:147], v[212:215], v[64:67]
	v_mfma_f32_16x16x32_bf16 v[0:3], v[152:155], v[212:215], v[0:3]
	v_mfma_f32_16x16x32_bf16 v[88:91], v[148:151], v[192:195], v[88:91]
	v_mfma_f32_16x16x32_bf16 v[20:23], v[156:159], v[192:195], v[20:23]
	v_mfma_f32_16x16x32_bf16 v[80:83], v[148:151], v[200:203], v[80:83]
	v_mfma_f32_16x16x32_bf16 v[16:19], v[156:159], v[200:203], v[16:19]
	v_mfma_f32_16x16x32_bf16 v[68:71], v[148:151], v[208:211], v[68:71]
	v_mfma_f32_16x16x32_bf16 v[4:7], v[156:159], v[208:211], v[4:7]
	v_mfma_f32_16x16x32_bf16 v[64:67], v[148:151], v[216:219], v[64:67]
	v_mfma_f32_16x16x32_bf16 v[0:3], v[156:159], v[216:219], v[0:3]
	s_barrier
	s_add_i32 s97, 0, 0x18000
	s_add_i32 vcc_lo, 0, 0x1c000
	v_add_u32_e32 v140, s97, v184
	v_add_u32_e32 v156, vcc_lo, v184
	ds_read_b128 v[128:131], v140
	ds_read_b128 v[132:135], v140 offset:1024
	ds_read_b128 v[136:139], v140 offset:2048
	ds_read_b128 v[140:143], v140 offset:3072
	ds_read_b128 v[144:147], v156
	ds_read_b128 v[148:151], v156 offset:1024
	ds_read_b128 v[152:155], v156 offset:2048
	ds_read_b128 v[156:159], v156 offset:3072
	s_add_u32 s50, s56, 0x100000
	s_addc_u32 s51, s57, 0
	s_mov_b32 m0, s69
	ds_read_b128 v[178:181], v189 offset:32768
	ds_read_b128 v[192:195], v189 offset:33792
	ds_read_b128 v[196:199], v189 offset:34816
	ds_read_b128 v[200:203], v189 offset:35840
	ds_read_b128 v[204:207], v189 offset:36864
	ds_read_b128 v[208:211], v189 offset:37888
	ds_read_b128 v[212:215], v189 offset:38912
	ds_read_b128 v[216:219], v189 offset:39936
	global_load_lds_dwordx4 v162, s[50:51]
	s_mov_b32 m0, s76
	s_nop 0
	global_load_lds_dwordx4 v166, s[50:51]
	s_waitcnt vmcnt(8)
	s_waitcnt lgkmcnt(0)
	s_barrier
	s_waitcnt lgkmcnt(0)
	v_mfma_f32_16x16x32_bf16 v[124:127], v[128:131], v[178:181], v[124:127]
	v_mfma_f32_16x16x32_bf16 v[60:63], v[136:139], v[178:181], v[60:63]
	v_mfma_f32_16x16x32_bf16 v[116:119], v[128:131], v[196:199], v[116:119]
	v_mfma_f32_16x16x32_bf16 v[56:59], v[136:139], v[196:199], v[56:59]
	v_mfma_f32_16x16x32_bf16 v[108:111], v[128:131], v[204:207], v[108:111]
	v_mfma_f32_16x16x32_bf16 v[44:47], v[136:139], v[204:207], v[44:47]
	v_mfma_f32_16x16x32_bf16 v[104:107], v[128:131], v[212:215], v[104:107]
	v_mfma_f32_16x16x32_bf16 v[40:43], v[136:139], v[212:215], v[40:43]
	v_mfma_f32_16x16x32_bf16 v[124:127], v[132:135], v[192:195], v[124:127]
	v_mfma_f32_16x16x32_bf16 v[60:63], v[140:143], v[192:195], v[60:63]
	v_mfma_f32_16x16x32_bf16 v[116:119], v[132:135], v[200:203], v[116:119]
	v_mfma_f32_16x16x32_bf16 v[56:59], v[140:143], v[200:203], v[56:59]
	v_mfma_f32_16x16x32_bf16 v[108:111], v[132:135], v[208:211], v[108:111]
	v_mfma_f32_16x16x32_bf16 v[44:47], v[140:143], v[208:211], v[44:47]
	v_mfma_f32_16x16x32_bf16 v[104:107], v[132:135], v[216:219], v[104:107]
	v_mfma_f32_16x16x32_bf16 v[40:43], v[140:143], v[216:219], v[40:43]
	v_mfma_f32_16x16x32_bf16 v[120:123], v[144:147], v[178:181], v[120:123]
	v_mfma_f32_16x16x32_bf16 v[52:55], v[152:155], v[178:181], v[52:55]
	v_mfma_f32_16x16x32_bf16 v[112:115], v[144:147], v[196:199], v[112:115]
	v_mfma_f32_16x16x32_bf16 v[48:51], v[152:155], v[196:199], v[48:51]
	v_mfma_f32_16x16x32_bf16 v[100:103], v[144:147], v[204:207], v[100:103]
	v_mfma_f32_16x16x32_bf16 v[36:39], v[152:155], v[204:207], v[36:39]
	v_mfma_f32_16x16x32_bf16 v[96:99], v[144:147], v[212:215], v[96:99]
	v_mfma_f32_16x16x32_bf16 v[32:35], v[152:155], v[212:215], v[32:35]
	v_mfma_f32_16x16x32_bf16 v[120:123], v[148:151], v[192:195], v[120:123]
	v_mfma_f32_16x16x32_bf16 v[52:55], v[156:159], v[192:195], v[52:55]
	v_mfma_f32_16x16x32_bf16 v[112:115], v[148:151], v[200:203], v[112:115]
	v_mfma_f32_16x16x32_bf16 v[48:51], v[156:159], v[200:203], v[48:51]
	v_mfma_f32_16x16x32_bf16 v[100:103], v[148:151], v[208:211], v[100:103]
	v_mfma_f32_16x16x32_bf16 v[36:39], v[156:159], v[208:211], v[36:39]
	v_mfma_f32_16x16x32_bf16 v[96:99], v[148:151], v[216:219], v[96:99]
	v_mfma_f32_16x16x32_bf16 v[32:35], v[156:159], v[216:219], v[32:35]
	s_barrier
	s_add_i32 s50, s97, s66
	s_mov_b32 m0, s50
	ds_read_b128 v[178:181], v189 offset:49152
	ds_read_b128 v[192:195], v189 offset:50176
	ds_read_b128 v[196:199], v189 offset:51200
	ds_read_b128 v[200:203], v189 offset:52224
	ds_read_b128 v[204:207], v189 offset:53248
	ds_read_b128 v[208:211], v189 offset:54272
	ds_read_b128 v[212:215], v189 offset:55296
	ds_read_b128 v[216:219], v189 offset:56320
	s_add_u32 s100, s54, 0x80
	s_addc_u32 s101, s55, 0
	global_load_lds_dwordx4 v164, s[100:101]
	s_add_i32 m0, s50, 0x2000
	s_add_u32 s50, s54, 0x100080
	v_lshl_add_u64 v[160:161], v[182:183], 0, s[10:11]
	s_addc_u32 s51, s55, 0
	s_add_i32 s54, vcc_lo, s66
	global_load_lds_dwordx4 v[160:161], off
	s_mov_b32 m0, s54
	s_nop 0
	global_load_lds_dwordx4 v164, s[50:51]
	s_add_i32 m0, s54, 0x2000
	s_nop 0
	global_load_lds_dwordx4 v168, s[50:51]
	s_mov_b32 m0, s84
	s_nop 0
	s_add_u32 s100, s56, 0x80
	s_addc_u32 s101, s57, 0
	global_load_lds_dwordx4 v162, s[100:101]
	s_mov_b32 m0, s85
	s_nop 0
	s_add_u32 s100, s56, 0x80
	s_addc_u32 s101, s57, 0
	global_load_lds_dwordx4 v166, s[100:101]
	s_add_i32 s96, s96, 2
	s_add_u32 s35, s35, 0x100
	s_addc_u32 s49, s49, 0
	s_cmp_gt_u32 s96, 61
	s_waitcnt vmcnt(8)
	s_waitcnt lgkmcnt(0)
	s_barrier
	s_waitcnt lgkmcnt(0)
	v_mfma_f32_16x16x32_bf16 v[92:95], v[128:131], v[178:181], v[92:95]
	v_mfma_f32_16x16x32_bf16 v[28:31], v[136:139], v[178:181], v[28:31]
	v_mfma_f32_16x16x32_bf16 v[84:87], v[128:131], v[196:199], v[84:87]
	v_mfma_f32_16x16x32_bf16 v[24:27], v[136:139], v[196:199], v[24:27]
	v_mfma_f32_16x16x32_bf16 v[76:79], v[128:131], v[204:207], v[76:79]
	v_mfma_f32_16x16x32_bf16 v[12:15], v[136:139], v[204:207], v[12:15]
	v_mfma_f32_16x16x32_bf16 v[72:75], v[128:131], v[212:215], v[72:75]
	v_mfma_f32_16x16x32_bf16 v[8:11], v[136:139], v[212:215], v[8:11]
	v_mfma_f32_16x16x32_bf16 v[92:95], v[132:135], v[192:195], v[92:95]
	v_mfma_f32_16x16x32_bf16 v[28:31], v[140:143], v[192:195], v[28:31]
	v_mfma_f32_16x16x32_bf16 v[84:87], v[132:135], v[200:203], v[84:87]
	v_mfma_f32_16x16x32_bf16 v[24:27], v[140:143], v[200:203], v[24:27]
	v_mfma_f32_16x16x32_bf16 v[76:79], v[132:135], v[208:211], v[76:79]
	v_mfma_f32_16x16x32_bf16 v[12:15], v[140:143], v[208:211], v[12:15]
	v_mfma_f32_16x16x32_bf16 v[72:75], v[132:135], v[216:219], v[72:75]
	v_mfma_f32_16x16x32_bf16 v[8:11], v[140:143], v[216:219], v[8:11]
	v_mfma_f32_16x16x32_bf16 v[88:91], v[144:147], v[178:181], v[88:91]
	v_mfma_f32_16x16x32_bf16 v[20:23], v[152:155], v[178:181], v[20:23]
	v_mfma_f32_16x16x32_bf16 v[80:83], v[144:147], v[196:199], v[80:83]
	v_mfma_f32_16x16x32_bf16 v[16:19], v[152:155], v[196:199], v[16:19]
	v_mfma_f32_16x16x32_bf16 v[68:71], v[144:147], v[204:207], v[68:71]
	v_mfma_f32_16x16x32_bf16 v[4:7], v[152:155], v[204:207], v[4:7]
	v_mfma_f32_16x16x32_bf16 v[64:67], v[144:147], v[212:215], v[64:67]
	v_mfma_f32_16x16x32_bf16 v[0:3], v[152:155], v[212:215], v[0:3]
	v_mfma_f32_16x16x32_bf16 v[88:91], v[148:151], v[192:195], v[88:91]
	v_mfma_f32_16x16x32_bf16 v[20:23], v[156:159], v[192:195], v[20:23]
	v_mfma_f32_16x16x32_bf16 v[80:83], v[148:151], v[200:203], v[80:83]
	v_mfma_f32_16x16x32_bf16 v[16:19], v[156:159], v[200:203], v[16:19]
	v_mfma_f32_16x16x32_bf16 v[68:71], v[148:151], v[208:211], v[68:71]
	v_mfma_f32_16x16x32_bf16 v[4:7], v[156:159], v[208:211], v[4:7]
	v_mfma_f32_16x16x32_bf16 v[64:67], v[148:151], v[216:219], v[64:67]
	v_mfma_f32_16x16x32_bf16 v[0:3], v[156:159], v[216:219], v[0:3]
	s_barrier
	s_mov_b64 s[50:51], s[52:53]
	s_cbranch_scc0 .LBB0_914
	s_setprio 0
	s_lshl_b32 s34, s46, 2
	v_lshl_or_b32 v178, s48, 7, v186
	s_add_i32 s34, s34, s65
	v_ashrrev_i32_e32 v179, 31, v178
	s_mul_hi_i32 s35, s34, 0x30000
	s_mul_i32 s39, s34, 0x30000
	v_lshlrev_b64 v[144:145], 2, v[178:179]
	v_readlane_b32 s24, v254, 31
	v_readlane_b32 s25, v254, 32
	v_readlane_b32 s26, v254, 33
	v_readlane_b32 s27, v254, 34
	v_lshl_add_u64 v[180:181], s[24:25], 0, v[144:145]
	v_lshl_add_u64 v[136:137], s[88:89], 0, v[144:145]
	global_load_dwordx4 v[128:131], v[180:181], off
	global_load_dwordx4 v[150:153], v[136:137], off
	v_lshl_add_u64 v[182:183], s[26:27], 0, v[144:145]
	v_lshl_add_u64 v[136:137], s[36:37], 0, v[144:145]
	global_load_dwordx4 v[132:135], v[182:183], off
	v_lshl_add_u64 v[140:141], s[58:59], 0, v[144:145]
	global_load_dwordx4 v[136:139], v[136:137], off
	v_lshl_add_u64 v[146:147], s[94:95], 0, v[144:145]
	global_load_dwordx4 v[140:143], v[140:141], off
	s_nop 0
	global_load_dwordx4 v[154:157], v[146:147], off
	v_lshl_add_u64 v[146:147], s[60:61], 0, v[144:145]
	v_lshl_add_u64 v[148:149], s[62:63], 0, v[144:145]
	global_load_dwordx4 v[144:147], v[146:147], off
	s_nop 0
	global_load_dwordx4 v[158:161], v[148:149], off
	s_and_saveexec_b64 s[48:49], s[0:1]
	s_cbranch_execz .LBB0_917
	s_add_u32 s50, s79, s39
	s_addc_u32 s51, s81, s35
	v_lshl_add_u64 v[248:249], v[178:179], 1, s[50:51]
	v_add_co_u32_e32 v250, vcc, s78, v248
	s_nop 2
	v_cvt_pk_bf16_f32 v244, v124, v125
	s_nop 2
	v_cvt_pk_bf16_f32 v245, v126, v127
	s_nop 2
	v_cvt_pk_bf16_f32 v246, v60, v61
	s_nop 2
	v_cvt_pk_bf16_f32 v247, v62, v63
	s_nop 1
	v_addc_co_u32_e32 v251, vcc, 0, v249, vcc
	s_mov_b32 s17, 0xc000
	global_store_dwordx4 v[248:249], v[244:247], off
	s_nop 1
	s_nop 2
	v_cvt_pk_bf16_f32 v244, v120, v121
	s_nop 2
	v_cvt_pk_bf16_f32 v245, v122, v123
	s_nop 2
	v_cvt_pk_bf16_f32 v246, v52, v53
	s_nop 2
	v_cvt_pk_bf16_f32 v247, v54, v55
	global_store_dwordx4 v[250:251], v[244:247], off
	v_add_co_u32_e32 v250, vcc, s17, v248
	s_nop 0
	s_nop 2
	v_cvt_pk_bf16_f32 v244, v116, v117
	s_nop 2
	v_cvt_pk_bf16_f32 v245, v118, v119
	s_nop 2
	v_cvt_pk_bf16_f32 v246, v56, v57
	s_nop 2
	v_cvt_pk_bf16_f32 v247, v58, v59
	s_nop 0
	v_addc_co_u32_e32 v251, vcc, 0, v249, vcc
	v_add_co_u32_e32 v248, vcc, 0x12000, v248
	global_store_dwordx4 v[250:251], v[244:247], off
	s_nop 0
	v_addc_co_u32_e32 v249, vcc, 0, v249, vcc
	s_nop 2
	v_cvt_pk_bf16_f32 v244, v112, v113
	s_nop 2
	v_cvt_pk_bf16_f32 v245, v114, v115
	s_nop 2
	v_cvt_pk_bf16_f32 v246, v48, v49
	s_nop 2
	v_cvt_pk_bf16_f32 v247, v50, v51
	global_store_dwordx4 v[248:249], v[244:247], off
.LBB0_917:
	s_or_b64 exec, exec, s[48:49]
	s_and_saveexec_b64 s[48:49], s[4:5]
	s_mov_b32 s96, s14
	s_cbranch_execz .LBB0_919
	s_add_u32 s50, s79, s39
	s_addc_u32 s51, s81, s35
	v_lshl_add_u64 v[248:249], v[178:179], 1, s[50:51]
	s_mov_b32 s14, 0x18000
	v_add_co_u32_e32 v250, vcc, s14, v248
	s_mov_b32 s14, 0x1e000
	s_nop 0
	v_addc_co_u32_e32 v251, vcc, 0, v249, vcc
	s_nop 2
	v_cvt_pk_bf16_f32 v244, v108, v109
	s_nop 2
	v_cvt_pk_bf16_f32 v245, v110, v111
	s_nop 2
	v_cvt_pk_bf16_f32 v246, v44, v45
	s_nop 2
	v_cvt_pk_bf16_f32 v247, v46, v47
	global_store_dwordx4 v[250:251], v[244:247], off
	v_add_co_u32_e32 v250, vcc, s14, v248
	s_mov_b32 s14, 0x24000
	s_nop 0
	v_addc_co_u32_e32 v251, vcc, 0, v249, vcc
	s_nop 2
	v_cvt_pk_bf16_f32 v244, v100, v101
	s_nop 2
	v_cvt_pk_bf16_f32 v245, v102, v103
	s_nop 2
	v_cvt_pk_bf16_f32 v246, v36, v37
	s_nop 2
	v_cvt_pk_bf16_f32 v247, v38, v39
	global_store_dwordx4 v[250:251], v[244:247], off
	v_add_co_u32_e32 v250, vcc, s14, v248
	s_nop 0
	s_nop 2
	v_cvt_pk_bf16_f32 v244, v104, v105
	s_nop 2
	v_cvt_pk_bf16_f32 v245, v106, v107
	s_nop 2
	v_cvt_pk_bf16_f32 v246, v40, v41
	s_nop 2
	v_cvt_pk_bf16_f32 v247, v42, v43
	s_nop 0
	v_addc_co_u32_e32 v251, vcc, 0, v249, vcc
	v_add_co_u32_e32 v248, vcc, 0x2a000, v248
	global_store_dwordx4 v[250:251], v[244:247], off
	s_nop 0
	v_addc_co_u32_e32 v249, vcc, 0, v249, vcc
	s_nop 2
	v_cvt_pk_bf16_f32 v244, v96, v97
	s_nop 2
	v_cvt_pk_bf16_f32 v245, v98, v99
	s_nop 2
	v_cvt_pk_bf16_f32 v246, v32, v33
	s_nop 2
	v_cvt_pk_bf16_f32 v247, v34, v35
	global_store_dwordx4 v[248:249], v[244:247], off
.LBB0_919:
	s_or_b64 exec, exec, s[48:49]
	s_add_i32 s35, s34, 2
	s_mul_hi_i32 s34, s35, 0x30000
	s_mul_i32 s35, s35, 0x30000
	s_and_saveexec_b64 s[48:49], s[0:1]
	s_cbranch_execz .LBB0_921
	s_add_u32 s50, s79, s35
	s_addc_u32 s51, s81, s34
	v_lshl_add_u64 v[248:249], v[178:179], 1, s[50:51]
	v_add_co_u32_e32 v250, vcc, s78, v248
	s_nop 2
	v_cvt_pk_bf16_f32 v244, v92, v93
	s_nop 2
	v_cvt_pk_bf16_f32 v245, v94, v95
	s_nop 2
	v_cvt_pk_bf16_f32 v246, v28, v29
	s_nop 2
	v_cvt_pk_bf16_f32 v247, v30, v31
	s_nop 1
	v_addc_co_u32_e32 v251, vcc, 0, v249, vcc
	s_mov_b32 s14, 0xc000
	global_store_dwordx4 v[248:249], v[244:247], off
	s_nop 1
	s_nop 2
	v_cvt_pk_bf16_f32 v244, v88, v89
	s_nop 2
	v_cvt_pk_bf16_f32 v245, v90, v91
	s_nop 2
	v_cvt_pk_bf16_f32 v246, v20, v21
	s_nop 2
	v_cvt_pk_bf16_f32 v247, v22, v23
	global_store_dwordx4 v[250:251], v[244:247], off
	v_add_co_u32_e32 v250, vcc, s14, v248
	s_nop 0
	s_nop 2
	v_cvt_pk_bf16_f32 v244, v84, v85
	s_nop 2
	v_cvt_pk_bf16_f32 v245, v86, v87
	s_nop 2
	v_cvt_pk_bf16_f32 v246, v24, v25
	s_nop 2
	v_cvt_pk_bf16_f32 v247, v26, v27
	s_nop 0
	v_addc_co_u32_e32 v251, vcc, 0, v249, vcc
	v_add_co_u32_e32 v248, vcc, 0x12000, v248
	global_store_dwordx4 v[250:251], v[244:247], off
	s_nop 0
	v_addc_co_u32_e32 v249, vcc, 0, v249, vcc
	s_nop 2
	v_cvt_pk_bf16_f32 v244, v80, v81
	s_nop 2
	v_cvt_pk_bf16_f32 v245, v82, v83
	s_nop 2
	v_cvt_pk_bf16_f32 v246, v16, v17
	s_nop 2
	v_cvt_pk_bf16_f32 v247, v18, v19
	global_store_dwordx4 v[248:249], v[244:247], off
.LBB0_921:
	s_or_b64 exec, exec, s[48:49]
	s_and_saveexec_b64 s[48:49], s[4:5]
	v_readlane_b32 s97, v254, 56
	s_mov_b32 s54, s16
	s_cbranch_execz .LBB0_923
	s_add_u32 s50, s79, s35
	s_addc_u32 s51, s81, s34
	v_lshl_add_u64 v[248:249], v[178:179], 1, s[50:51]
	s_mov_b32 s14, 0x18000
	v_add_co_u32_e32 v250, vcc, s14, v248
	s_mov_b32 s14, 0x1e000
	s_nop 0
	v_addc_co_u32_e32 v251, vcc, 0, v249, vcc
	s_nop 2
	v_cvt_pk_bf16_f32 v244, v76, v77
	s_nop 2
	v_cvt_pk_bf16_f32 v245, v78, v79
	s_nop 2
	v_cvt_pk_bf16_f32 v246, v12, v13
	s_nop 2
	v_cvt_pk_bf16_f32 v247, v14, v15
	global_store_dwordx4 v[250:251], v[244:247], off
	v_add_co_u32_e32 v250, vcc, s14, v248
	s_mov_b32 s14, 0x24000
	s_nop 0
	v_addc_co_u32_e32 v251, vcc, 0, v249, vcc
	s_nop 2
	v_cvt_pk_bf16_f32 v244, v68, v69
	s_nop 2
	v_cvt_pk_bf16_f32 v245, v70, v71
	s_nop 2
	v_cvt_pk_bf16_f32 v246, v4, v5
	s_nop 2
	v_cvt_pk_bf16_f32 v247, v6, v7
	global_store_dwordx4 v[250:251], v[244:247], off
	v_add_co_u32_e32 v250, vcc, s14, v248
	s_nop 0
	s_nop 2
	v_cvt_pk_bf16_f32 v244, v72, v73
	s_nop 2
	v_cvt_pk_bf16_f32 v245, v74, v75
	s_nop 2
	v_cvt_pk_bf16_f32 v246, v8, v9
	s_nop 2
	v_cvt_pk_bf16_f32 v247, v10, v11
	s_nop 0
	v_addc_co_u32_e32 v251, vcc, 0, v249, vcc
	v_add_co_u32_e32 v248, vcc, 0x2a000, v248
	global_store_dwordx4 v[250:251], v[244:247], off
	s_nop 0
	v_addc_co_u32_e32 v249, vcc, 0, v249, vcc
	s_nop 2
	v_cvt_pk_bf16_f32 v244, v64, v65
	s_nop 2
	v_cvt_pk_bf16_f32 v245, v66, v67
	s_nop 2
	v_cvt_pk_bf16_f32 v246, v0, v1
	s_nop 2
	v_cvt_pk_bf16_f32 v247, v2, v3
	global_store_dwordx4 v[248:249], v[244:247], off
.LBB0_923:
	s_or_b64 exec, exec, s[48:49]
	v_readlane_b32 s16, v254, 23
	v_mov_b32_dpp v194, v97 row_ror:1 row_mask:0xf bank_mask:0xf bound_ctrl:1
	v_mov_b32_dpp v193, v96 row_ror:1 row_mask:0xf bank_mask:0xf bound_ctrl:1
	v_mov_b32_dpp v148, v104 row_ror:1 row_mask:0xf bank_mask:0xf bound_ctrl:1
	v_mov_b32_dpp v197, v124 row_ror:15 row_mask:0xf bank_mask:0xf bound_ctrl:1
	v_mov_b32_dpp v201, v120 row_ror:15 row_mask:0xf bank_mask:0xf bound_ctrl:1
	v_mov_b32_dpp v149, v105 row_ror:1 row_mask:0xf bank_mask:0xf bound_ctrl:1
	v_mov_b32_dpp v202, v121 row_ror:15 row_mask:0xf bank_mask:0xf bound_ctrl:1
	v_mov_b32_dpp v195, v98 row_ror:1 row_mask:0xf bank_mask:0xf bound_ctrl:1
	v_mov_b32_dpp v196, v99 row_ror:1 row_mask:0xf bank_mask:0xf bound_ctrl:1
	v_mov_b32_dpp v203, v122 row_ror:15 row_mask:0xf bank_mask:0xf bound_ctrl:1
	v_mov_b32_dpp v198, v125 row_ror:15 row_mask:0xf bank_mask:0xf bound_ctrl:1
	v_mov_b32_dpp v204, v123 row_ror:15 row_mask:0xf bank_mask:0xf bound_ctrl:1
	v_mov_b32_dpp v191, v106 row_ror:1 row_mask:0xf bank_mask:0xf bound_ctrl:1
	v_mov_b32_dpp v199, v126 row_ror:15 row_mask:0xf bank_mask:0xf bound_ctrl:1
	v_mov_b32_dpp v192, v107 row_ror:1 row_mask:0xf bank_mask:0xf bound_ctrl:1
	v_mov_b32_dpp v200, v127 row_ror:15 row_mask:0xf bank_mask:0xf bound_ctrl:1
	v_readlane_b32 s17, v254, 24
	v_readlane_b32 s18, v254, 25
	v_readlane_b32 s19, v254, 26
	v_readlane_b32 s20, v254, 27
	v_readlane_b32 s21, v254, 28
	v_readlane_b32 s22, v254, 29
	v_readlane_b32 s23, v254, 30
	v_readlane_b32 s28, v254, 35
	v_readlane_b32 s29, v254, 36
	v_readlane_b32 s30, v254, 37
	v_readlane_b32 s31, v254, 38
	s_waitcnt vmcnt(16)
	v_fma_f32 v148, v128, v148, v132
	v_fma_f32 v205, v124, v128, v132
	v_fma_f32 v194, v151, v194, v137
	v_fma_f32 v193, v150, v193, v136
	v_fmac_f32_e32 v194, v121, v155
	v_fmac_f32_e32 v193, v120, v154
	v_fmac_f32_e32 v148, v124, v140
	v_fmac_f32_e32 v194, v113, v159
	v_fmac_f32_e32 v193, v112, v158
	v_mul_f32_e32 v124, v194, v194
	v_fma_f32 v206, v120, v150, v136
	v_mul_f32_e32 v120, v193, v193
	v_fmamk_f32 v124, v124, 0xbdd2d3e7, v190
	v_fmamk_f32 v120, v120, 0xbdd2d3e7, v190
	v_mul_f32_e32 v124, v194, v124
	v_mul_f32_e32 v120, v193, v120
	v_exp_f32_e32 v124, v124
	v_exp_f32_e32 v120, v120
	v_fma_f32 v149, v129, v149, v133
	v_fmac_f32_e32 v149, v125, v141
	v_add_f32_e32 v124, 1.0, v124
	v_add_f32_e32 v120, 1.0, v120
	v_rcp_f32_e32 v124, v124
	v_rcp_f32_e32 v120, v120
	v_fma_f32 v121, v121, v151, v137
	v_fmac_f32_e32 v149, v117, v145
	v_mul_f32_e32 v124, v194, v124
	v_fmac_f32_e32 v121, v113, v155
	v_fmac_f32_e32 v148, v116, v144
	v_mul_f32_e32 v120, v193, v120
	v_mul_f32_e32 v124, v149, v124
	v_fmac_f32_e32 v121, v101, v159
	v_mul_f32_e32 v120, v148, v120
	v_cvt_pk_bf16_f32 v148, v120, v124
	v_mul_f32_e32 v124, v121, v121
	v_fmamk_f32 v124, v124, 0xbdd2d3e7, v190
	v_mul_f32_e32 v124, v121, v124
	v_exp_f32_e32 v124, v124
	v_fma_f32 v195, v152, v195, v138
	v_fmac_f32_e32 v195, v122, v156
	v_fma_f32 v122, v122, v152, v138
	v_add_f32_e32 v124, 1.0, v124
	v_rcp_f32_e32 v124, v124
	v_fma_f32 v196, v153, v196, v139
	v_fmac_f32_e32 v206, v112, v154
	v_fmac_f32_e32 v122, v114, v156
	v_fmac_f32_e32 v196, v123, v157
	v_fmac_f32_e32 v195, v114, v160
	v_fmac_f32_e32 v206, v100, v158
	v_fmac_f32_e32 v122, v102, v160
	v_fmac_f32_e32 v196, v115, v161
	v_mul_f32_e32 v207, v195, v195
	v_mul_f32_e32 v209, v206, v206
	v_mul_f32_e32 v121, v121, v124
	v_mul_f32_e32 v124, v122, v122
	v_mul_f32_e32 v208, v196, v196
	v_fmamk_f32 v207, v207, 0xbdd2d3e7, v190
	v_fmamk_f32 v209, v209, 0xbdd2d3e7, v190
	v_fmamk_f32 v124, v124, 0xbdd2d3e7, v190
	v_fmamk_f32 v208, v208, 0xbdd2d3e7, v190
	v_mul_f32_e32 v207, v195, v207
	v_mul_f32_e32 v209, v206, v209
	v_fma_f32 v125, v125, v129, v133
	v_mul_f32_e32 v124, v122, v124
	v_fma_f32 v123, v123, v153, v139
	v_mul_f32_e32 v208, v196, v208
	v_exp_f32_e32 v207, v207
	v_exp_f32_e32 v209, v209
	v_fmac_f32_e32 v125, v117, v141
	v_exp_f32_e32 v124, v124
	v_fmac_f32_e32 v123, v115, v157
	v_fma_f32 v191, v130, v191, v134
	v_exp_f32_e32 v208, v208
	v_fmac_f32_e32 v125, v109, v145
	v_fmac_f32_e32 v123, v103, v161
	v_fmac_f32_e32 v191, v126, v142
	v_mul_f32_e32 v121, v125, v121
	v_fma_f32 v125, v126, v130, v134
	v_mul_f32_e32 v126, v123, v123
	v_fmamk_f32 v126, v126, 0xbdd2d3e7, v190
	v_add_f32_e32 v207, 1.0, v207
	v_add_f32_e32 v120, 1.0, v209
	v_add_f32_e32 v124, 1.0, v124
	v_mul_f32_e32 v126, v123, v126
	v_add_f32_e32 v208, 1.0, v208
	v_rcp_f32_e32 v207, v207
	v_rcp_f32_e32 v120, v120
	v_rcp_f32_e32 v124, v124
	v_exp_f32_e32 v126, v126
	v_rcp_f32_e32 v208, v208
	v_fma_f32 v113, v113, v151, v137
	v_fma_f32 v192, v131, v192, v135
	v_fmac_f32_e32 v205, v116, v140
	v_fma_f32 v112, v112, v150, v136
	v_fmac_f32_e32 v113, v101, v155
	v_fma_f32 v101, v101, v151, v137
	v_fmac_f32_e32 v192, v127, v143
	v_fmac_f32_e32 v191, v118, v146
	v_mul_f32_e32 v193, v195, v207
	v_fmac_f32_e32 v205, v108, v144
	v_mul_f32_e32 v120, v206, v120
	v_mul_f32_e32 v122, v122, v124
	v_add_f32_e32 v124, 1.0, v126
	v_fmac_f32_e32 v112, v100, v154
	v_fmac_f32_e32 v101, v97, v155
	v_fmac_f32_e32 v192, v119, v147
	v_mul_f32_e32 v194, v196, v208
	v_mul_f32_e32 v149, v191, v193
	v_mul_f32_e32 v120, v205, v120
	v_rcp_f32_e32 v124, v124
	v_fmac_f32_e32 v112, v96, v158
	v_fmac_f32_e32 v101, v159, v202
	v_mul_f32_e32 v191, v192, v194
	v_cvt_pk_bf16_f32 v149, v149, v191
	v_fmac_f32_e32 v125, v118, v142
	v_cvt_pk_bf16_f32 v120, v120, v121
	v_mul_f32_e32 v121, v112, v112
	v_fmac_f32_e32 v113, v97, v159
	v_mul_f32_e32 v97, v101, v101
	v_fmac_f32_e32 v125, v110, v146
	v_fmamk_f32 v121, v121, 0xbdd2d3e7, v190
	v_fmamk_f32 v97, v97, 0xbdd2d3e7, v190
	v_mul_f32_e32 v122, v125, v122
	v_fma_f32 v125, v127, v131, v135
	v_mul_f32_e32 v121, v112, v121
	v_mul_f32_e32 v97, v101, v97
	v_fmac_f32_e32 v125, v119, v143
	v_mul_f32_e32 v123, v123, v124
	v_exp_f32_e32 v124, v121
	v_exp_f32_e32 v97, v97
	v_fmac_f32_e32 v125, v111, v147
	v_mul_f32_e32 v123, v125, v123
	v_cvt_pk_bf16_f32 v121, v122, v123
	v_mul_f32_e32 v123, v113, v113
	v_add_f32_e32 v122, 1.0, v124
	v_fmamk_f32 v123, v123, 0xbdd2d3e7, v190
	v_fma_f32 v100, v100, v150, v136
	v_add_f32_e32 v97, 1.0, v97
	v_rcp_f32_e32 v122, v122
	v_mul_f32_e32 v123, v113, v123
	v_fmac_f32_e32 v100, v96, v154
	v_rcp_f32_e32 v97, v97
	v_exp_f32_e32 v123, v123
	v_fmac_f32_e32 v100, v158, v201
	v_fma_f32 v116, v116, v128, v132
	v_mul_f32_e32 v96, v100, v100
	v_fmac_f32_e32 v116, v108, v140
	v_fmamk_f32 v96, v96, 0xbdd2d3e7, v190
	v_fmac_f32_e32 v116, v104, v144
	v_mul_f32_e32 v112, v112, v122
	v_mul_f32_e32 v96, v100, v96
	v_mul_f32_e32 v97, v101, v97
	v_fma_f32 v101, v102, v152, v138
	v_mul_f32_e32 v112, v116, v112
	v_add_f32_e32 v116, 1.0, v123
	v_fma_f32 v114, v114, v152, v138
	v_exp_f32_e32 v96, v96
	v_fmac_f32_e32 v101, v98, v156
	v_rcp_f32_e32 v116, v116
	v_fmac_f32_e32 v114, v102, v156
	v_fmac_f32_e32 v101, v160, v203
	v_fmac_f32_e32 v114, v98, v160
	v_mul_f32_e32 v98, v101, v101
	v_fmamk_f32 v98, v98, 0xbdd2d3e7, v190
	v_add_f32_e32 v96, 1.0, v96
	v_mul_f32_e32 v98, v101, v98
	v_mul_f32_e32 v113, v113, v116
	v_mul_f32_e32 v116, v114, v114
	v_rcp_f32_e32 v96, v96
	v_exp_f32_e32 v98, v98
	v_fma_f32 v102, v103, v153, v139
	v_fmamk_f32 v116, v116, 0xbdd2d3e7, v190
	v_fma_f32 v115, v115, v153, v139
	v_fmac_f32_e32 v102, v99, v157
	v_fma_f32 v117, v117, v129, v133
	v_mul_f32_e32 v116, v114, v116
	v_fmac_f32_e32 v115, v103, v157
	v_fmac_f32_e32 v102, v161, v204
	v_fmac_f32_e32 v117, v109, v141
	v_exp_f32_e32 v116, v116
	v_fmac_f32_e32 v115, v99, v161
	v_mul_f32_e32 v99, v102, v102
	v_fmac_f32_e32 v117, v105, v145
	v_mul_f32_e32 v96, v100, v96
	v_fma_f32 v100, v109, v129, v133
	v_add_f32_e32 v98, 1.0, v98
	v_fmamk_f32 v99, v99, 0xbdd2d3e7, v190
	v_mul_f32_e32 v113, v117, v113
	v_fma_f32 v117, v118, v130, v134
	v_mul_f32_e32 v118, v115, v115
	v_fmac_f32_e32 v100, v105, v141
	v_rcp_f32_e32 v98, v98
	v_mul_f32_e32 v99, v102, v99
	v_fmamk_f32 v118, v118, 0xbdd2d3e7, v190
	v_fmac_f32_e32 v100, v145, v198
	v_exp_f32_e32 v99, v99
	v_add_f32_e32 v116, 1.0, v116
	v_mul_f32_e32 v118, v115, v118
	v_mul_f32_e32 v97, v100, v97
	v_fma_f32 v100, v110, v130, v134
	v_rcp_f32_e32 v116, v116
	v_exp_f32_e32 v118, v118
	v_fmac_f32_e32 v100, v106, v142
	v_fmac_f32_e32 v100, v146, v199
	v_mul_f32_e32 v98, v101, v98
	v_mul_f32_e32 v100, v100, v98
	v_add_f32_e32 v98, 1.0, v99
	v_rcp_f32_e32 v98, v98
	v_mul_f32_e32 v114, v114, v116
	v_add_f32_e32 v116, 1.0, v118
	v_fmac_f32_e32 v117, v110, v142
	v_rcp_f32_e32 v116, v116
	v_fmac_f32_e32 v117, v106, v146
	v_mul_f32_e32 v114, v117, v114
	v_fma_f32 v117, v119, v131, v135
	v_mul_f32_e32 v98, v102, v98
	v_mov_b32_dpp v102, v64 row_ror:1 row_mask:0xf bank_mask:0xf bound_ctrl:1
	v_fmac_f32_e32 v117, v111, v143
	v_fma_f32 v102, v150, v102, v136
	v_fmac_f32_e32 v117, v107, v147
	v_mul_f32_e32 v115, v115, v116
	v_fmac_f32_e32 v102, v88, v154
	v_mul_f32_e32 v115, v117, v115
	v_fmac_f32_e32 v102, v80, v158
	v_cvt_pk_bf16_f32 v112, v112, v113
	v_cvt_pk_bf16_f32 v113, v114, v115
	v_mul_f32_e32 v115, v102, v102
	v_fmamk_f32 v115, v115, 0xbdd2d3e7, v190
	v_mov_b32_dpp v103, v65 row_ror:1 row_mask:0xf bank_mask:0xf bound_ctrl:1
	v_mul_f32_e32 v115, v102, v115
	v_exp_f32_e32 v115, v115
	v_fma_f32 v103, v151, v103, v137
	v_fmac_f32_e32 v103, v89, v155
	v_fma_f32 v108, v108, v128, v132
	v_fmac_f32_e32 v103, v81, v159
	v_fmac_f32_e32 v108, v104, v140
	v_fma_f32 v99, v111, v131, v135
	v_mul_f32_e32 v117, v103, v103
	v_fmac_f32_e32 v108, v144, v197
	v_fmac_f32_e32 v99, v107, v143
	v_add_f32_e32 v115, 1.0, v115
	v_fmamk_f32 v117, v117, 0xbdd2d3e7, v190
	v_mul_f32_e32 v96, v108, v96
	v_fmac_f32_e32 v99, v147, v200
	v_rcp_f32_e32 v115, v115
	v_mul_f32_e32 v117, v103, v117
	v_mul_f32_e32 v99, v99, v98
	v_cvt_pk_bf16_f32 v98, v96, v97
	v_mov_b32_dpp v96, v72 row_ror:1 row_mask:0xf bank_mask:0xf bound_ctrl:1
	v_exp_f32_e32 v117, v117
	v_fma_f32 v96, v128, v96, v132
	v_fmac_f32_e32 v96, v92, v140
	v_fmac_f32_e32 v96, v84, v144
	v_mul_f32_e32 v102, v102, v115
	v_mul_f32_e32 v96, v96, v102
	v_add_f32_e32 v102, 1.0, v117
	v_rcp_f32_e32 v102, v102
	v_mov_b32_dpp v104, v66 row_ror:1 row_mask:0xf bank_mask:0xf bound_ctrl:1
	v_mov_b32_dpp v97, v73 row_ror:1 row_mask:0xf bank_mask:0xf bound_ctrl:1
	v_fma_f32 v97, v129, v97, v133
	v_mul_f32_e32 v102, v103, v102
	v_fma_f32 v103, v152, v104, v138
	v_fmac_f32_e32 v103, v90, v156
	v_fmac_f32_e32 v103, v82, v160
	v_mul_f32_e32 v104, v103, v103
	v_fmamk_f32 v104, v104, 0xbdd2d3e7, v190
	v_mul_f32_e32 v104, v103, v104
	v_exp_f32_e32 v104, v104
	v_fmac_f32_e32 v97, v93, v141
	v_mov_b32_dpp v105, v67 row_ror:1 row_mask:0xf bank_mask:0xf bound_ctrl:1
	v_fmac_f32_e32 v97, v85, v145
	v_mul_f32_e32 v97, v97, v102
	v_add_f32_e32 v102, 1.0, v104
	v_fma_f32 v104, v153, v105, v139
	v_fmac_f32_e32 v104, v91, v157
	v_fmac_f32_e32 v104, v83, v161
	v_mul_f32_e32 v105, v104, v104
	v_fmamk_f32 v105, v105, 0xbdd2d3e7, v190
	v_rcp_f32_e32 v102, v102
	v_mul_f32_e32 v105, v104, v105
	v_cvt_pk_bf16_f32 v99, v100, v99
	v_mov_b32_dpp v100, v74 row_ror:1 row_mask:0xf bank_mask:0xf bound_ctrl:1
	v_exp_f32_e32 v105, v105
	v_fma_f32 v100, v130, v100, v134
	v_fmac_f32_e32 v100, v94, v142
	v_fmac_f32_e32 v100, v86, v146
	v_mul_f32_e32 v102, v103, v102
	v_mov_b32_dpp v110, v88 row_ror:15 row_mask:0xf bank_mask:0xf bound_ctrl:1
	v_mul_f32_e32 v100, v100, v102
	v_add_f32_e32 v102, 1.0, v105
	v_fma_f32 v88, v88, v150, v136
	v_rcp_f32_e32 v102, v102
	v_fmac_f32_e32 v88, v80, v154
	v_mov_b32_dpp v101, v75 row_ror:1 row_mask:0xf bank_mask:0xf bound_ctrl:1
	v_fmac_f32_e32 v88, v68, v158
	v_fma_f32 v101, v131, v101, v135
	v_cvt_pk_bf16_f32 v96, v96, v97
	v_mul_f32_e32 v97, v88, v88
	v_fmac_f32_e32 v101, v95, v143
	v_fmamk_f32 v97, v97, 0xbdd2d3e7, v190
	v_fmac_f32_e32 v101, v87, v147
	v_mul_f32_e32 v102, v104, v102
	v_mul_f32_e32 v97, v88, v97
	v_mov_b32_dpp v111, v89 row_ror:15 row_mask:0xf bank_mask:0xf bound_ctrl:1
	v_mul_f32_e32 v101, v101, v102
	v_exp_f32_e32 v102, v97
	v_fma_f32 v89, v89, v151, v137
	v_fmac_f32_e32 v89, v81, v155
	v_fmac_f32_e32 v89, v69, v159
	v_cvt_pk_bf16_f32 v97, v100, v101
	v_mul_f32_e32 v101, v89, v89
	v_add_f32_e32 v100, 1.0, v102
	v_fmamk_f32 v101, v101, 0xbdd2d3e7, v190
	v_rcp_f32_e32 v100, v100
	v_mul_f32_e32 v101, v89, v101
	v_exp_f32_e32 v101, v101
	v_mov_b32_dpp v106, v92 row_ror:15 row_mask:0xf bank_mask:0xf bound_ctrl:1
	v_fma_f32 v92, v92, v128, v132
	v_fmac_f32_e32 v92, v84, v140
	v_fmac_f32_e32 v92, v76, v144
	v_mul_f32_e32 v88, v88, v100
	v_mul_f32_e32 v88, v92, v88
	v_add_f32_e32 v92, 1.0, v101
	v_rcp_f32_e32 v92, v92
	v_mov_b32_dpp v114, v90 row_ror:15 row_mask:0xf bank_mask:0xf bound_ctrl:1
	v_fma_f32 v90, v90, v152, v138
	v_fmac_f32_e32 v90, v82, v156
	v_fmac_f32_e32 v90, v70, v160
	v_mul_f32_e32 v89, v89, v92
	v_mul_f32_e32 v92, v90, v90
	v_fmamk_f32 v92, v92, 0xbdd2d3e7, v190
	v_mov_b32_dpp v107, v93 row_ror:15 row_mask:0xf bank_mask:0xf bound_ctrl:1
	v_mov_b32_dpp v116, v91 row_ror:15 row_mask:0xf bank_mask:0xf bound_ctrl:1
	v_fma_f32 v93, v93, v129, v133
	v_mul_f32_e32 v92, v90, v92
	v_fma_f32 v91, v91, v153, v139
	v_fmac_f32_e32 v93, v85, v141
	v_exp_f32_e32 v92, v92
	v_fmac_f32_e32 v91, v83, v157
	v_fmac_f32_e32 v93, v77, v145
	v_fmac_f32_e32 v91, v71, v161
	v_mov_b32_dpp v108, v94 row_ror:15 row_mask:0xf bank_mask:0xf bound_ctrl:1
	v_mul_f32_e32 v89, v93, v89
	v_fma_f32 v93, v94, v130, v134
	v_mul_f32_e32 v94, v91, v91
	v_fmamk_f32 v94, v94, 0xbdd2d3e7, v190
	v_add_f32_e32 v92, 1.0, v92
	v_mul_f32_e32 v94, v91, v94
	v_rcp_f32_e32 v92, v92
	v_exp_f32_e32 v94, v94
	v_fma_f32 v80, v80, v150, v136
	v_fmac_f32_e32 v80, v68, v154
	v_mul_f32_e32 v90, v90, v92
	v_add_f32_e32 v92, 1.0, v94
	v_rcp_f32_e32 v92, v92
	v_fmac_f32_e32 v80, v64, v158
	v_fmac_f32_e32 v93, v86, v142
	v_cvt_pk_bf16_f32 v88, v88, v89
	v_mul_f32_e32 v89, v80, v80
	v_fmac_f32_e32 v93, v78, v146
	v_fmamk_f32 v89, v89, 0xbdd2d3e7, v190
	v_mul_f32_e32 v90, v93, v90
	v_fma_f32 v93, v95, v131, v135
	v_mul_f32_e32 v89, v80, v89
	v_fmac_f32_e32 v93, v87, v143
	v_mul_f32_e32 v91, v91, v92
	v_exp_f32_e32 v92, v89
	v_fma_f32 v81, v81, v151, v137
	v_fmac_f32_e32 v93, v79, v147
	v_fmac_f32_e32 v81, v69, v155
	v_fma_f32 v69, v69, v151, v137
	v_mul_f32_e32 v91, v93, v91
	v_fmac_f32_e32 v81, v65, v159
	v_fmac_f32_e32 v69, v65, v155
	v_cvt_pk_bf16_f32 v89, v90, v91
	v_mul_f32_e32 v91, v81, v81
	v_fmac_f32_e32 v69, v159, v111
	v_add_f32_e32 v90, 1.0, v92
	v_fmamk_f32 v91, v91, 0xbdd2d3e7, v190
	v_mul_f32_e32 v65, v69, v69
	v_rcp_f32_e32 v90, v90
	v_mul_f32_e32 v91, v81, v91
	v_fmamk_f32 v65, v65, 0xbdd2d3e7, v190
	v_exp_f32_e32 v91, v91
	v_mul_f32_e32 v65, v69, v65
	v_fma_f32 v84, v84, v128, v132
	v_exp_f32_e32 v65, v65
	v_fmac_f32_e32 v84, v76, v140
	v_fmac_f32_e32 v84, v72, v144
	v_mul_f32_e32 v80, v80, v90
	v_mul_f32_e32 v80, v84, v80
	v_add_f32_e32 v84, 1.0, v91
	v_rcp_f32_e32 v84, v84
	v_fma_f32 v68, v68, v150, v136
	v_add_f32_e32 v65, 1.0, v65
	v_fma_f32 v82, v82, v152, v138
	v_fmac_f32_e32 v68, v64, v154
	v_rcp_f32_e32 v65, v65
	v_fmac_f32_e32 v82, v70, v156
	v_fmac_f32_e32 v68, v158, v110
	v_fmac_f32_e32 v82, v66, v160
	v_mul_f32_e32 v64, v68, v68
	v_mul_f32_e32 v81, v81, v84
	v_mul_f32_e32 v84, v82, v82
	v_fmamk_f32 v64, v64, 0xbdd2d3e7, v190
	v_fmamk_f32 v84, v84, 0xbdd2d3e7, v190
	v_mul_f32_e32 v64, v68, v64
	v_mul_f32_e32 v65, v69, v65
	v_fma_f32 v69, v70, v152, v138
	v_fma_f32 v85, v85, v129, v133
	v_mul_f32_e32 v84, v82, v84
	v_fma_f32 v83, v83, v153, v139
	v_exp_f32_e32 v64, v64
	v_fmac_f32_e32 v69, v66, v156
	v_fmac_f32_e32 v139, v71, v153
	v_fmac_f32_e32 v85, v77, v141
	v_exp_f32_e32 v84, v84
	v_fmac_f32_e32 v83, v71, v157
	v_fmac_f32_e32 v69, v160, v114
	v_fmac_f32_e32 v139, v67, v157
	v_fmac_f32_e32 v85, v73, v145
	v_fmac_f32_e32 v83, v67, v161
	v_mul_f32_e32 v66, v69, v69
	v_fmac_f32_e32 v139, v161, v116
	v_mul_f32_e32 v81, v85, v81
	v_fma_f32 v85, v86, v130, v134
	v_mul_f32_e32 v86, v83, v83
	v_fmamk_f32 v66, v66, 0xbdd2d3e7, v190
	v_mul_f32_e32 v67, v139, v139
	v_fmamk_f32 v86, v86, 0xbdd2d3e7, v190
	v_add_f32_e32 v64, 1.0, v64
	v_mul_f32_e32 v66, v69, v66
	v_fmamk_f32 v67, v67, 0xbdd2d3e7, v190
	v_add_f32_e32 v84, 1.0, v84
	v_mul_f32_e32 v86, v83, v86
	v_rcp_f32_e32 v64, v64
	v_exp_f32_e32 v66, v66
	v_mul_f32_e32 v67, v139, v67
	v_rcp_f32_e32 v84, v84
	v_exp_f32_e32 v86, v86
	v_exp_f32_e32 v67, v67
	v_mul_f32_e32 v64, v68, v64
	v_fma_f32 v68, v77, v129, v133
	v_add_f32_e32 v66, 1.0, v66
	v_mul_f32_e32 v82, v82, v84
	v_add_f32_e32 v84, 1.0, v86
	v_fmac_f32_e32 v68, v73, v141
	v_rcp_f32_e32 v66, v66
	v_add_f32_e32 v67, 1.0, v67
	v_fmac_f32_e32 v85, v78, v142
	v_rcp_f32_e32 v84, v84
	v_fmac_f32_e32 v68, v145, v107
	v_rcp_f32_e32 v67, v67
	v_fmac_f32_e32 v85, v74, v146
	v_fma_f32 v76, v76, v128, v132
	v_mul_f32_e32 v65, v68, v65
	v_fma_f32 v68, v78, v130, v134
	v_mul_f32_e32 v82, v85, v82
	v_fma_f32 v85, v87, v131, v135
	v_fmac_f32_e32 v76, v72, v140
	v_fmac_f32_e32 v68, v74, v142
	v_fmac_f32_e32 v135, v79, v131
	v_mov_b32_dpp v109, v95 row_ror:15 row_mask:0xf bank_mask:0xf bound_ctrl:1
	v_fmac_f32_e32 v85, v79, v143
	v_fmac_f32_e32 v76, v144, v106
	v_fmac_f32_e32 v68, v146, v108
	v_mul_f32_e32 v66, v69, v66
	v_fmac_f32_e32 v135, v75, v143
	v_fmac_f32_e32 v85, v75, v147
	v_mul_f32_e32 v83, v83, v84
	v_mul_f32_e32 v64, v76, v64
	v_mul_f32_e32 v66, v68, v66
	v_fmac_f32_e32 v135, v147, v109
	v_mul_f32_e32 v67, v139, v67
	v_mul_f32_e32 v83, v85, v83
	v_cvt_pk_bf16_f32 v80, v80, v81
	v_cvt_pk_bf16_f32 v81, v82, v83
	v_mul_f32_e32 v67, v135, v67
	v_cvt_pk_bf16_f32 v64, v64, v65
	v_cvt_pk_bf16_f32 v65, v66, v67
	v_or_b32_e32 v66, 4, v178
	v_ashrrev_i32_e32 v67, 31, v66
	v_lshlrev_b64 v[78:79], 2, v[66:67]
	v_lshl_add_u64 v[66:67], s[88:89], 0, v[78:79]
	v_lshl_add_u64 v[68:69], s[94:95], 0, v[78:79]
	global_load_dwordx4 v[106:109], v[66:67], off
	global_load_dwordx4 v[102:105], v[68:69], off
	v_lshl_add_u64 v[66:67], s[36:37], 0, v[78:79]
	global_load_dwordx4 v[66:69], v[66:67], off
	v_lshl_add_u64 v[70:71], s[62:63], 0, v[78:79]
	global_load_dwordx4 v[116:119], v[70:71], off
	global_load_dwordx4 v[74:77], v[180:181], off offset:16
	v_lshl_add_u64 v[82:83], s[58:59], 0, v[78:79]
	global_load_dwordx4 v[70:73], v[182:183], off offset:16
	global_load_dwordx4 v[84:87], v[82:83], off
	v_lshl_add_u64 v[78:79], s[60:61], 0, v[78:79]
	global_load_dwordx4 v[92:95], v[78:79], off
	v_mov_b32_dpp v100, v32 row_ror:1 row_mask:0xf bank_mask:0xf bound_ctrl:1
	v_mov_b32_dpp v110, v33 row_ror:1 row_mask:0xf bank_mask:0xf bound_ctrl:1
	v_mov_b32_dpp v78, v40 row_ror:1 row_mask:0xf bank_mask:0xf bound_ctrl:1
	v_mov_b32_dpp v111, v34 row_ror:1 row_mask:0xf bank_mask:0xf bound_ctrl:1
	v_mov_b32_dpp v79, v41 row_ror:1 row_mask:0xf bank_mask:0xf bound_ctrl:1
	v_mov_b32_dpp v114, v35 row_ror:1 row_mask:0xf bank_mask:0xf bound_ctrl:1
	v_mov_b32_dpp v82, v42 row_ror:1 row_mask:0xf bank_mask:0xf bound_ctrl:1
	v_mov_b32_dpp v83, v43 row_ror:1 row_mask:0xf bank_mask:0xf bound_ctrl:1
	v_lshl_add_u32 v140, s46, 8, v185
	v_mov_b32_dpp v142, v60 row_ror:15 row_mask:0xf bank_mask:0xf bound_ctrl:1
	v_mov_b32_dpp v141, v61 row_ror:15 row_mask:0xf bank_mask:0xf bound_ctrl:1
	v_mov_b32_dpp v91, v62 row_ror:15 row_mask:0xf bank_mask:0xf bound_ctrl:1
	v_mov_b32_dpp v90, v63 row_ror:15 row_mask:0xf bank_mask:0xf bound_ctrl:1
	v_mov_b32_dpp v144, v52 row_ror:15 row_mask:0xf bank_mask:0xf bound_ctrl:1
	v_mov_b32_dpp v143, v53 row_ror:15 row_mask:0xf bank_mask:0xf bound_ctrl:1
	v_mov_b32_dpp v101, v54 row_ror:15 row_mask:0xf bank_mask:0xf bound_ctrl:1
	s_waitcnt vmcnt(5)
	v_fma_f32 v115, v106, v100, v66
	v_fmac_f32_e32 v115, v52, v102
	s_waitcnt vmcnt(4)
	v_fmac_f32_e32 v115, v48, v116
	v_mul_f32_e32 v100, v115, v115
	v_fmamk_f32 v100, v100, 0xbdd2d3e7, v190
	v_mul_f32_e32 v100, v115, v100
	v_exp_f32_e32 v122, v100
	v_fma_f32 v110, v107, v110, v67
	v_fmac_f32_e32 v110, v53, v103
	v_fmac_f32_e32 v110, v49, v117
	v_mul_f32_e32 v123, v110, v110
	v_add_f32_e32 v122, 1.0, v122
	v_fmamk_f32 v123, v123, 0xbdd2d3e7, v190
	v_rcp_f32_e32 v122, v122
	v_mul_f32_e32 v123, v110, v123
	v_exp_f32_e32 v123, v123
	s_waitcnt vmcnt(2)
	v_fma_f32 v78, v74, v78, v70
	s_waitcnt vmcnt(1)
	v_fmac_f32_e32 v78, v60, v84
	s_waitcnt vmcnt(0)
	v_fmac_f32_e32 v78, v56, v92
	v_mul_f32_e32 v115, v115, v122
	v_mul_f32_e32 v78, v78, v115
	v_add_f32_e32 v115, 1.0, v123
	v_rcp_f32_e32 v115, v115
	v_fma_f32 v111, v108, v111, v68
	v_fmac_f32_e32 v111, v54, v104
	v_fmac_f32_e32 v111, v50, v118
	v_mul_f32_e32 v110, v110, v115
	v_mul_f32_e32 v115, v111, v111
	v_fmamk_f32 v115, v115, 0xbdd2d3e7, v190
	v_mul_f32_e32 v115, v111, v115
	v_exp_f32_e32 v115, v115
	v_fma_f32 v79, v75, v79, v71
	v_fma_f32 v114, v109, v114, v69
	v_fmac_f32_e32 v79, v61, v85
	v_fmac_f32_e32 v114, v55, v105
	v_fmac_f32_e32 v79, v57, v93
	v_fmac_f32_e32 v114, v51, v119
	v_mul_f32_e32 v79, v79, v110
	v_add_f32_e32 v110, 1.0, v115
	v_mul_f32_e32 v115, v114, v114
	v_fmamk_f32 v115, v115, 0xbdd2d3e7, v190
	v_rcp_f32_e32 v110, v110
	v_mul_f32_e32 v115, v114, v115
	v_exp_f32_e32 v115, v115
	v_fma_f32 v82, v76, v82, v72
	v_fmac_f32_e32 v82, v62, v86
	v_fmac_f32_e32 v82, v58, v94
	v_mul_f32_e32 v110, v111, v110
	v_mul_f32_e32 v82, v82, v110
	v_add_f32_e32 v110, 1.0, v115
	v_rcp_f32_e32 v110, v110
	v_fma_f32 v83, v77, v83, v73
	v_fmac_f32_e32 v83, v63, v87
	v_mov_b32_dpp v100, v55 row_ror:15 row_mask:0xf bank_mask:0xf bound_ctrl:1
	v_fmac_f32_e32 v83, v59, v95
	v_mul_f32_e32 v110, v114, v110
	v_mul_f32_e32 v83, v83, v110
	v_cvt_pk_bf16_f32 v150, v78, v79
	v_cvt_pk_bf16_f32 v151, v82, v83
	s_and_saveexec_b64 s[46:47], s[2:3]
	s_cbranch_execz .LBB0_925
	v_mov_b64_e32 v[78:79], s[12:13]
	v_mad_i64_i32 v[78:79], s[34:35], v140, s78, v[78:79]
	v_lshl_add_u64 v[78:79], v[178:179], 1, v[78:79]
	global_store_dwordx4 v[78:79], v[148:151], off
